# diff-attention unit epilogue: the 15 serialized g_head load/wait/store steps replaced by 15 loads hoisted behind the first one and a single wait; on top of batched prologue loads and the pipelined att
# speedup vs baseline: 1.0102x; 1.0015x over previous
; __device__ __forceinline__ unsigned cvtpk(float lo, float hi) { f32x2_t v = {lo, hi}; bf16x2_t b = __builtin_convertvector(v, bf16x2_t); return __builtin_bit_cast(unsigned, b); }
; __device__ __forceinline__ void diff_combine(LAS unsigned char* lds, f32x16 (&O)[4], float lsum, float lam, int slot, int comp, const float* ghead, bf16* mixrow  , bool store) {
;     ...
;     __syncthreads();
;     if (comp == 0) {
;         float ss = 0.f;
; #pragma unroll
;         for (int b = 0; b < 4; ++b)
; #pragma unroll
;             for (int i = 0; i < 16; ++i) { const float o = O[b][i] * inv - X[(b * 16 + i) * 64 + lane]; O[b][i] = o; ss += o * o; }
;         ss += __shfl_xor(ss, 32);
;         const float rn = 0.8f / sqrtf(ss * (1.0f / 128.0f) + NORM_EPS);
;         if (store) {
; #pragma unroll
;             for (int b = 0; b < 4; ++b)
; #pragma unroll
;                 for (int g4 = 0; g4 < 4; ++g4) {
;                     const int d = 32 * b + 8 * g4 + 4 * h;
;                     const f32x4 gv = *(const f32x4*)(ghead + d);
;                     *(u32x2*)(mixrow + d) = (u32x2){cvtpk(O[b][4 * g4] * rn * gv[0], O[b][4 * g4 + 1] * rn * gv[1]), cvtpk(O[b][4 * g4 + 2] * rn * gv[2], O[b][4 * g4 + 3] * rn * gv[3])};
.LBB0_498:
	s_andn2_b64 vcc, exec, s[24:25]
	s_waitcnt lgkmcnt(0)
	s_barrier
	s_cbranch_vccnz .LBB0_451
	ds_read2st64_b32 v[72:73], v214 offset1:1
	ds_read2st64_b32 v[74:75], v214 offset0:2 offset1:3
	ds_read2st64_b32 v[76:77], v214 offset0:4 offset1:5
	ds_read2st64_b32 v[78:79], v214 offset0:6 offset1:7
	ds_read2st64_b32 v[80:81], v214 offset0:8 offset1:9
	ds_read2st64_b32 v[82:83], v214 offset0:10 offset1:11
	ds_read2st64_b32 v[84:85], v214 offset0:12 offset1:13
	ds_read2st64_b32 v[86:87], v214 offset0:14 offset1:15
	ds_read2st64_b32 v[88:89], v214 offset0:16 offset1:17
	ds_read2st64_b32 v[90:91], v214 offset0:18 offset1:19
	ds_read2st64_b32 v[92:93], v214 offset0:20 offset1:21
	ds_read2st64_b32 v[94:95], v214 offset0:22 offset1:23
	ds_read2st64_b32 v[96:97], v214 offset0:24 offset1:25
	ds_read2st64_b32 v[98:99], v214 offset0:26 offset1:27
	ds_read2st64_b32 v[100:101], v214 offset0:28 offset1:29
	ds_read2st64_b32 v[102:103], v214 offset0:30 offset1:31
	ds_read2st64_b32 v[104:105], v214 offset0:32 offset1:33
	ds_read2st64_b32 v[106:107], v214 offset0:34 offset1:35
	ds_read2st64_b32 v[108:109], v214 offset0:36 offset1:37
	ds_read2st64_b32 v[110:111], v214 offset0:38 offset1:39
	ds_read2st64_b32 v[112:113], v214 offset0:40 offset1:41
	ds_read2st64_b32 v[114:115], v214 offset0:42 offset1:43
	ds_read2st64_b32 v[116:117], v214 offset0:44 offset1:45
	ds_read2st64_b32 v[118:119], v214 offset0:46 offset1:47
	ds_read2st64_b32 v[66:67], v214 offset0:58 offset1:59
	ds_read2st64_b32 v[120:121], v214 offset0:48 offset1:49
	ds_read2st64_b32 v[122:123], v214 offset0:50 offset1:51
	ds_read2st64_b32 v[124:125], v214 offset0:52 offset1:53
	ds_read2st64_b32 v[126:127], v214 offset0:54 offset1:55
	ds_read2st64_b32 v[128:129], v214 offset0:60 offset1:61
	ds_read2st64_b32 v[192:193], v214 offset0:62 offset1:63
	ds_read2st64_b32 v[194:195], v214 offset0:56 offset1:57
	s_waitcnt lgkmcnt(14)
	v_pk_fma_f32 v[52:53], v[52:53], v[70:71], v[74:75] op_sel_hi:[1,0,1] neg_lo:[0,0,1] neg_hi:[0,0,1]
	v_pk_fma_f32 v[74:75], v[50:51], v[70:71], v[72:73] op_sel_hi:[1,0,1] neg_lo:[0,0,1] neg_hi:[0,0,1]
	v_pk_mul_f32 v[220:221], v[52:53], v[52:53]
	v_pk_mul_f32 v[222:223], v[74:75], v[74:75]
	v_pk_fma_f32 v[72:73], v[56:57], v[70:71], v[78:79] op_sel_hi:[1,0,1] neg_lo:[0,0,1] neg_hi:[0,0,1]
	v_add_f32_e32 v1, v222, v223
	v_pk_fma_f32 v[78:79], v[54:55], v[70:71], v[76:77] op_sel_hi:[1,0,1] neg_lo:[0,0,1] neg_hi:[0,0,1]
	v_add_f32_e32 v1, v1, v220
	v_pk_mul_f32 v[226:227], v[78:79], v[78:79]
	v_add_f32_e32 v1, v1, v221
	v_add_f32_e32 v1, v1, v226
	v_pk_mul_f32 v[224:225], v[72:73], v[72:73]
	v_add_f32_e32 v1, v1, v227
	v_pk_fma_f32 v[80:81], v[58:59], v[70:71], v[80:81] op_sel_hi:[1,0,1] neg_lo:[0,0,1] neg_hi:[0,0,1]
	v_add_f32_e32 v1, v1, v224
	v_pk_mul_f32 v[228:229], v[80:81], v[80:81]
	v_add_f32_e32 v1, v1, v225
	v_pk_fma_f32 v[60:61], v[60:61], v[70:71], v[82:83] op_sel_hi:[1,0,1] neg_lo:[0,0,1] neg_hi:[0,0,1]
	v_add_f32_e32 v1, v1, v228
	v_pk_mul_f32 v[82:83], v[60:61], v[60:61]
	v_add_f32_e32 v1, v1, v229
	v_pk_fma_f32 v[76:77], v[62:63], v[70:71], v[84:85] op_sel_hi:[1,0,1] neg_lo:[0,0,1] neg_hi:[0,0,1]
	v_add_f32_e32 v1, v1, v82
	v_pk_mul_f32 v[84:85], v[76:77], v[76:77]
	v_add_f32_e32 v1, v1, v83
	v_pk_fma_f32 v[56:57], v[64:65], v[70:71], v[86:87] op_sel_hi:[1,0,1] neg_lo:[0,0,1] neg_hi:[0,0,1]
	v_add_f32_e32 v1, v1, v84
	v_pk_mul_f32 v[86:87], v[56:57], v[56:57]
	v_add_f32_e32 v1, v1, v85
	v_pk_fma_f32 v[64:65], v[34:35], v[70:71], v[88:89] op_sel_hi:[1,0,1] neg_lo:[0,0,1] neg_hi:[0,0,1]
	v_add_f32_e32 v1, v1, v86
	v_pk_mul_f32 v[88:89], v[64:65], v[64:65]
	v_add_f32_e32 v1, v1, v87
	v_pk_fma_f32 v[54:55], v[36:37], v[70:71], v[90:91] op_sel_hi:[1,0,1] neg_lo:[0,0,1] neg_hi:[0,0,1]
	v_add_f32_e32 v1, v1, v88
	v_pk_mul_f32 v[90:91], v[54:55], v[54:55]
	v_add_f32_e32 v1, v1, v89
	v_pk_fma_f32 v[62:63], v[38:39], v[70:71], v[92:93] op_sel_hi:[1,0,1] neg_lo:[0,0,1] neg_hi:[0,0,1]
	v_add_f32_e32 v1, v1, v90
	v_pk_mul_f32 v[92:93], v[62:63], v[62:63]
	v_add_f32_e32 v1, v1, v91
	s_waitcnt lgkmcnt(7)
	v_pk_fma_f32 v[68:69], v[12:13], v[70:71], v[66:67] op_sel_hi:[1,0,1] neg_lo:[0,0,1] neg_hi:[0,0,1]
	s_waitcnt lgkmcnt(2)
	v_pk_fma_f32 v[66:67], v[14:15], v[70:71], v[128:129] op_sel_hi:[1,0,1] neg_lo:[0,0,1] neg_hi:[0,0,1]
	global_load_dwordx4 v[12:15], v[142:143], off
	global_load_dwordx4 v[164:167], v[142:143], off offset:32
	global_load_dwordx4 v[168:171], v[142:143], off offset:64
	global_load_dwordx4 v[172:175], v[142:143], off offset:96
	global_load_dwordx4 v[176:179], v[142:143], off offset:128
	global_load_dwordx4 v[180:183], v[142:143], off offset:160
	global_load_dwordx4 v[184:187], v[142:143], off offset:192
	global_load_dwordx4 v[230:233], v[142:143], off offset:224
	global_load_dwordx4 v[234:237], v[142:143], off offset:256
	global_load_dwordx4 v[238:241], v[142:143], off offset:288
	global_load_dwordx4 v[242:245], v[142:143], off offset:320
	global_load_dwordx4 v[246:249], v[142:143], off offset:352
	global_load_dwordx4 v[252:255], v[142:143], off offset:384
	global_load_dwordx4 v[150:153], v[142:143], off offset:416
	global_load_dwordx4 v[220:223], v[142:143], off offset:448
	global_load_dwordx4 v[224:227], v[142:143], off offset:480
	v_pk_fma_f32 v[50:51], v[40:41], v[70:71], v[94:95] op_sel_hi:[1,0,1] neg_lo:[0,0,1] neg_hi:[0,0,1]
	v_add_f32_e32 v1, v1, v92
	v_pk_mul_f32 v[94:95], v[50:51], v[50:51]
	v_add_f32_e32 v1, v1, v93
	v_pk_fma_f32 v[58:59], v[42:43], v[70:71], v[96:97] op_sel_hi:[1,0,1] neg_lo:[0,0,1] neg_hi:[0,0,1]
	v_add_f32_e32 v1, v1, v94
	v_pk_mul_f32 v[96:97], v[58:59], v[58:59]
	v_add_f32_e32 v1, v1, v95
; __device__ __forceinline__ unsigned cvtpk(float lo, float hi) { f32x2_t v = {lo, hi}; bf16x2_t b = __builtin_convertvector(v, bf16x2_t); return __builtin_bit_cast(unsigned, b); }
; __device__ __forceinline__ void diff_combine(LAS unsigned char* lds, f32x16 (&O)[4], float lsum, float lam, int slot, int comp, const float* ghead, bf16* mixrow  , bool store) {
;     ...
;             for (int i = 0; i < 16; ++i) { const float o = O[b][i] * inv - X[(b * 16 + i) * 64 + lane]; O[b][i] = o; ss += o * o; }
;         ss += __shfl_xor(ss, 32);
;         const float rn = 0.8f / sqrtf(ss * (1.0f / 128.0f) + NORM_EPS);
;         if (store) {
; #pragma unroll
;             for (int b = 0; b < 4; ++b)
; #pragma unroll
;                 for (int g4 = 0; g4 < 4; ++g4) {
;                     const int d = 32 * b + 8 * g4 + 4 * h;
;                     const f32x4 gv = *(const f32x4*)(ghead + d);
;                     *(u32x2*)(mixrow + d) = (u32x2){cvtpk(O[b][4 * g4] * rn * gv[0], O[b][4 * g4 + 1] * rn * gv[1]), cvtpk(O[b][4 * g4 + 2] * rn * gv[2], O[b][4 * g4 + 3] * rn * gv[3])};
	v_pk_fma_f32 v[38:39], v[44:45], v[70:71], v[98:99] op_sel_hi:[1,0,1] neg_lo:[0,0,1] neg_hi:[0,0,1]
	v_add_f32_e32 v1, v1, v96
	v_pk_mul_f32 v[98:99], v[38:39], v[38:39]
	v_add_f32_e32 v1, v1, v97
	v_pk_fma_f32 v[46:47], v[46:47], v[70:71], v[100:101] op_sel_hi:[1,0,1] neg_lo:[0,0,1] neg_hi:[0,0,1]
	v_add_f32_e32 v1, v1, v98
	v_pk_mul_f32 v[100:101], v[46:47], v[46:47]
	v_add_f32_e32 v1, v1, v99
	v_pk_fma_f32 v[36:37], v[48:49], v[70:71], v[102:103] op_sel_hi:[1,0,1] neg_lo:[0,0,1] neg_hi:[0,0,1]
	v_add_f32_e32 v1, v1, v100
	v_pk_mul_f32 v[48:49], v[36:37], v[36:37]
	v_add_f32_e32 v1, v1, v101
	v_pk_fma_f32 v[44:45], v[18:19], v[70:71], v[104:105] op_sel_hi:[1,0,1] neg_lo:[0,0,1] neg_hi:[0,0,1]
	v_add_f32_e32 v1, v1, v48
	v_pk_mul_f32 v[104:105], v[44:45], v[44:45]
	v_add_f32_e32 v1, v1, v49
	v_pk_fma_f32 v[34:35], v[20:21], v[70:71], v[106:107] op_sel_hi:[1,0,1] neg_lo:[0,0,1] neg_hi:[0,0,1]
	v_add_f32_e32 v1, v1, v104
	v_pk_mul_f32 v[102:103], v[34:35], v[34:35]
	v_add_f32_e32 v1, v1, v105
	v_pk_fma_f32 v[42:43], v[22:23], v[70:71], v[108:109] op_sel_hi:[1,0,1] neg_lo:[0,0,1] neg_hi:[0,0,1]
	v_add_f32_e32 v1, v1, v102
	v_pk_mul_f32 v[108:109], v[42:43], v[42:43]
	v_add_f32_e32 v1, v1, v103
	v_pk_fma_f32 v[24:25], v[24:25], v[70:71], v[110:111] op_sel_hi:[1,0,1] neg_lo:[0,0,1] neg_hi:[0,0,1]
	v_add_f32_e32 v1, v1, v108
	v_pk_mul_f32 v[106:107], v[24:25], v[24:25]
	v_add_f32_e32 v1, v1, v109
	v_pk_fma_f32 v[40:41], v[26:27], v[70:71], v[112:113] op_sel_hi:[1,0,1] neg_lo:[0,0,1] neg_hi:[0,0,1]
	v_add_f32_e32 v1, v1, v106
	v_pk_mul_f32 v[112:113], v[40:41], v[40:41]
	v_add_f32_e32 v1, v1, v107
	v_pk_fma_f32 v[22:23], v[28:29], v[70:71], v[114:115] op_sel_hi:[1,0,1] neg_lo:[0,0,1] neg_hi:[0,0,1]
	v_add_f32_e32 v1, v1, v112
	v_pk_mul_f32 v[110:111], v[22:23], v[22:23]
	v_add_f32_e32 v1, v1, v113
	v_pk_fma_f32 v[28:29], v[30:31], v[70:71], v[116:117] op_sel_hi:[1,0,1] neg_lo:[0,0,1] neg_hi:[0,0,1]
	v_add_f32_e32 v1, v1, v110
	v_pk_mul_f32 v[30:31], v[28:29], v[28:29]
	v_add_f32_e32 v1, v1, v111
	v_pk_fma_f32 v[20:21], v[32:33], v[70:71], v[118:119] op_sel_hi:[1,0,1] neg_lo:[0,0,1] neg_hi:[0,0,1]
	v_add_f32_e32 v1, v1, v30
	v_pk_mul_f32 v[32:33], v[20:21], v[20:21]
	v_add_f32_e32 v1, v1, v31
	v_pk_fma_f32 v[26:27], v[2:3], v[70:71], v[120:121] op_sel_hi:[1,0,1] neg_lo:[0,0,1] neg_hi:[0,0,1]
	v_add_f32_e32 v1, v1, v32
	v_pk_mul_f32 v[116:117], v[26:27], v[26:27]
	v_add_f32_e32 v1, v1, v33
	v_pk_fma_f32 v[18:19], v[4:5], v[70:71], v[122:123] op_sel_hi:[1,0,1] neg_lo:[0,0,1] neg_hi:[0,0,1]
	v_add_f32_e32 v1, v1, v116
	v_pk_mul_f32 v[114:115], v[18:19], v[18:19]
	v_add_f32_e32 v1, v1, v117
	v_pk_fma_f32 v[6:7], v[6:7], v[70:71], v[124:125] op_sel_hi:[1,0,1] neg_lo:[0,0,1] neg_hi:[0,0,1]
	v_add_f32_e32 v1, v1, v114
	v_pk_mul_f32 v[118:119], v[6:7], v[6:7]
	v_add_f32_e32 v1, v1, v115
	v_pk_fma_f32 v[2:3], v[8:9], v[70:71], v[126:127] op_sel_hi:[1,0,1] neg_lo:[0,0,1] neg_hi:[0,0,1]
	v_add_f32_e32 v1, v1, v118
	v_pk_mul_f32 v[8:9], v[2:3], v[2:3]
	v_add_f32_e32 v1, v1, v119
	s_waitcnt lgkmcnt(0)
	v_pk_fma_f32 v[4:5], v[10:11], v[70:71], v[194:195] op_sel_hi:[1,0,1] neg_lo:[0,0,1] neg_hi:[0,0,1]
	v_add_f32_e32 v1, v1, v8
	v_pk_mul_f32 v[10:11], v[4:5], v[4:5]
	v_add_f32_e32 v1, v1, v9
	v_add_f32_e32 v1, v1, v10
	v_pk_mul_f32 v[218:219], v[68:69], v[68:69]
	v_add_f32_e32 v1, v1, v11
	v_add_f32_e32 v1, v1, v218
	v_pk_mul_f32 v[128:129], v[66:67], v[66:67]
	v_add_f32_e32 v1, v1, v219
	v_pk_fma_f32 v[16:17], v[16:17], v[70:71], v[192:193] op_sel_hi:[1,0,1] neg_lo:[0,0,1] neg_hi:[0,0,1]
	v_add_f32_e32 v1, v1, v128
	v_pk_mul_f32 v[192:193], v[16:17], v[16:17]
	v_add_f32_e32 v1, v1, v129
	v_add_f32_e32 v1, v1, v192
	v_add_f32_e32 v1, v1, v193
	ds_bpermute_b32 v8, v201, v1
	s_mov_b32 s0, 0xf800000
	s_waitcnt lgkmcnt(0)
	v_add_f32_e32 v1, v1, v8
	v_fmamk_f32 v1, v1, 0x3c000000, v215
	v_mul_f32_e32 v8, 0x4f800000, v1
	v_cmp_gt_f32_e32 vcc, s0, v1
	s_nop 1
	v_cndmask_b32_e32 v1, v1, v8, vcc
	v_sqrt_f32_e32 v8, v1
	s_nop 0
	v_add_u32_e32 v9, -1, v8
	v_fma_f32 v10, -v9, v8, v1
	v_cmp_ge_f32_e64 s[0:1], 0, v10
	v_add_u32_e32 v10, 1, v8
	s_nop 0
	v_cndmask_b32_e64 v9, v8, v9, s[0:1]
	v_fma_f32 v8, -v10, v8, v1
	v_cmp_lt_f32_e64 s[0:1], 0, v8
	s_nop 1
	v_cndmask_b32_e64 v8, v9, v10, s[0:1]
	v_mul_f32_e32 v9, 0x37800000, v8
	v_cndmask_b32_e32 v8, v8, v9, vcc
	v_cmp_class_f32_e32 vcc, v1, v216
	s_nop 1
	v_cndmask_b32_e32 v1, v8, v1, vcc
	v_div_scale_f32 v10, s[0:1], v1, v1, s87
	v_rcp_f32_e32 v11, v10
	v_lshlrev_b64 v[8:9], 11, v[190:191]
	v_lshl_add_u64 v[30:31], v[188:189], 0, v[8:9]
	v_fma_f32 v8, -v10, v11, 1.0
	v_fmac_f32_e32 v11, v8, v11
	v_div_scale_f32 v8, vcc, s87, v1, s87
	v_mul_f32_e32 v9, v8, v11
	v_fma_f32 v32, -v10, v9, v8
	v_fmac_f32_e32 v9, v32, v11
	v_fma_f32 v8, -v10, v9, v8
	v_div_fmas_f32 v8, v8, v11, v9
	v_div_fixup_f32 v32, v8, v1, s87
	v_pk_mul_f32 v[8:9], v[74:75], v[32:33] op_sel_hi:[1,0]
	v_pk_mul_f32 v[10:11], v[52:53], v[32:33] op_sel_hi:[1,0]
	s_waitcnt vmcnt(0)
; __device__ __forceinline__ unsigned cvtpk(float lo, float hi) { f32x2_t v = {lo, hi}; bf16x2_t b = __builtin_convertvector(v, bf16x2_t); return __builtin_bit_cast(unsigned, b); }
; __device__ __forceinline__ void diff_combine(LAS unsigned char* lds, f32x16 (&O)[4], float lsum, float lam, int slot, int comp, const float* ghead, bf16* mixrow  , bool store) {
;     ...
;         if (store) {
; #pragma unroll
;             for (int b = 0; b < 4; ++b)
; #pragma unroll
;                 for (int g4 = 0; g4 < 4; ++g4) {
;                     const int d = 32 * b + 8 * g4 + 4 * h;
;                     const f32x4 gv = *(const f32x4*)(ghead + d);
;                     *(u32x2*)(mixrow + d) = (u32x2){cvtpk(O[b][4 * g4] * rn * gv[0], O[b][4 * g4 + 1] * rn * gv[1]), cvtpk(O[b][4 * g4 + 2] * rn * gv[2], O[b][4 * g4 + 3] * rn * gv[3])};
;                 }
	v_pk_mul_f32 v[8:9], v[12:13], v[8:9]
	v_pk_mul_f32 v[10:11], v[14:15], v[10:11]
	v_cvt_pk_bf16_f32 v8, v8, v9
	v_cvt_pk_bf16_f32 v9, v10, v11
	global_store_dwordx2 v[30:31], v[8:9], off
	v_pk_mul_f32 v[12:13], v[78:79], v[32:33] op_sel_hi:[1,0]
	v_pk_mul_f32 v[14:15], v[60:61], v[32:33] op_sel_hi:[1,0]
	v_pk_mul_f32 v[6:7], v[6:7], v[32:33] op_sel_hi:[1,0]
	v_pk_mul_f32 v[2:3], v[2:3], v[32:33] op_sel_hi:[1,0]
	v_pk_mul_f32 v[8:9], v[164:165], v[12:13]
	v_pk_mul_f32 v[12:13], v[72:73], v[32:33] op_sel_hi:[1, 0]
	v_cvt_pk_bf16_f32 v8, v8, v9
	v_pk_mul_f32 v[10:11], v[166:167], v[12:13]
	v_pk_mul_f32 v[12:13], v[80:81], v[32:33] op_sel_hi:[1, 0]
	v_cvt_pk_bf16_f32 v9, v10, v11
	global_store_dwordx2 v[30:31], v[8:9], off offset:16
	v_pk_mul_f32 v[8:9], v[168:169], v[12:13]
	v_pk_mul_f32 v[10:11], v[170:171], v[14:15]
	v_cvt_pk_bf16_f32 v8, v8, v9
	v_cvt_pk_bf16_f32 v9, v10, v11
	global_store_dwordx2 v[30:31], v[8:9], off offset:32
	v_pk_mul_f32 v[12:13], v[76:77], v[32:33] op_sel_hi:[1,0]
	v_pk_mul_f32 v[14:15], v[56:57], v[32:33] op_sel_hi:[1,0]
	v_pk_mul_f32 v[8:9], v[172:173], v[12:13]
	v_pk_mul_f32 v[10:11], v[174:175], v[14:15]
	v_cvt_pk_bf16_f32 v8, v8, v9
	v_cvt_pk_bf16_f32 v9, v10, v11
	global_store_dwordx2 v[30:31], v[8:9], off offset:48
	v_pk_mul_f32 v[12:13], v[64:65], v[32:33] op_sel_hi:[1,0]
	v_pk_mul_f32 v[14:15], v[54:55], v[32:33] op_sel_hi:[1,0]
	v_pk_mul_f32 v[8:9], v[12:13], v[176:177]
	v_pk_mul_f32 v[10:11], v[14:15], v[178:179]
	v_cvt_pk_bf16_f32 v8, v8, v9
	v_cvt_pk_bf16_f32 v9, v10, v11
	global_store_dwordx2 v[30:31], v[8:9], off offset:64
	v_pk_mul_f32 v[12:13], v[62:63], v[32:33] op_sel_hi:[1,0]
	v_pk_mul_f32 v[14:15], v[50:51], v[32:33] op_sel_hi:[1,0]
	v_pk_mul_f32 v[8:9], v[12:13], v[180:181]
	v_pk_mul_f32 v[10:11], v[14:15], v[182:183]
	v_cvt_pk_bf16_f32 v8, v8, v9
	v_cvt_pk_bf16_f32 v9, v10, v11
	global_store_dwordx2 v[30:31], v[8:9], off offset:80
	v_pk_mul_f32 v[12:13], v[58:59], v[32:33] op_sel_hi:[1,0]
	v_pk_mul_f32 v[14:15], v[38:39], v[32:33] op_sel_hi:[1,0]
	v_pk_mul_f32 v[8:9], v[12:13], v[184:185]
	v_pk_mul_f32 v[10:11], v[14:15], v[186:187]
	v_cvt_pk_bf16_f32 v8, v8, v9
	v_cvt_pk_bf16_f32 v9, v10, v11
	global_store_dwordx2 v[30:31], v[8:9], off offset:96
	v_pk_mul_f32 v[12:13], v[46:47], v[32:33] op_sel_hi:[1,0]
	v_pk_mul_f32 v[14:15], v[36:37], v[32:33] op_sel_hi:[1,0]
	v_pk_mul_f32 v[8:9], v[12:13], v[230:231]
	v_pk_mul_f32 v[10:11], v[14:15], v[232:233]
	v_cvt_pk_bf16_f32 v8, v8, v9
	v_cvt_pk_bf16_f32 v9, v10, v11
	global_store_dwordx2 v[30:31], v[8:9], off offset:112
	v_pk_mul_f32 v[12:13], v[44:45], v[32:33] op_sel_hi:[1,0]
	v_pk_mul_f32 v[14:15], v[34:35], v[32:33] op_sel_hi:[1,0]
	v_pk_mul_f32 v[8:9], v[12:13], v[234:235]
	v_pk_mul_f32 v[10:11], v[14:15], v[236:237]
	v_cvt_pk_bf16_f32 v8, v8, v9
	v_cvt_pk_bf16_f32 v9, v10, v11
	global_store_dwordx2 v[30:31], v[8:9], off offset:128
	v_pk_mul_f32 v[12:13], v[42:43], v[32:33] op_sel_hi:[1,0]
	v_pk_mul_f32 v[14:15], v[24:25], v[32:33] op_sel_hi:[1,0]
	v_pk_mul_f32 v[8:9], v[12:13], v[238:239]
	v_pk_mul_f32 v[10:11], v[14:15], v[240:241]
	v_cvt_pk_bf16_f32 v8, v8, v9
	v_cvt_pk_bf16_f32 v9, v10, v11
	global_store_dwordx2 v[30:31], v[8:9], off offset:144
	v_pk_mul_f32 v[12:13], v[40:41], v[32:33] op_sel_hi:[1,0]
	v_pk_mul_f32 v[14:15], v[22:23], v[32:33] op_sel_hi:[1,0]
	v_pk_mul_f32 v[8:9], v[12:13], v[242:243]
	v_pk_mul_f32 v[10:11], v[14:15], v[244:245]
	v_cvt_pk_bf16_f32 v8, v8, v9
	v_cvt_pk_bf16_f32 v9, v10, v11
	global_store_dwordx2 v[30:31], v[8:9], off offset:160
	v_pk_mul_f32 v[12:13], v[28:29], v[32:33] op_sel_hi:[1,0]
	v_pk_mul_f32 v[14:15], v[20:21], v[32:33] op_sel_hi:[1,0]
	v_pk_mul_f32 v[8:9], v[12:13], v[246:247]
	v_pk_mul_f32 v[10:11], v[14:15], v[248:249]
	v_cvt_pk_bf16_f32 v8, v8, v9
	v_cvt_pk_bf16_f32 v9, v10, v11
	global_store_dwordx2 v[30:31], v[8:9], off offset:176
	v_pk_mul_f32 v[12:13], v[26:27], v[32:33] op_sel_hi:[1,0]
	v_pk_mul_f32 v[14:15], v[18:19], v[32:33] op_sel_hi:[1,0]
	v_pk_mul_f32 v[8:9], v[12:13], v[252:253]
	v_pk_mul_f32 v[10:11], v[14:15], v[254:255]
	v_cvt_pk_bf16_f32 v8, v8, v9
	v_cvt_pk_bf16_f32 v9, v10, v11
	global_store_dwordx2 v[30:31], v[8:9], off offset:192
	v_pk_mul_f32 v[6:7], v[6:7], v[150:151]
	v_pk_mul_f32 v[2:3], v[2:3], v[152:153]
	v_cvt_pk_bf16_f32 v6, v6, v7
	v_cvt_pk_bf16_f32 v7, v2, v3
	global_store_dwordx2 v[30:31], v[6:7], off offset:208
	v_pk_mul_f32 v[2:3], v[4:5], v[32:33] op_sel_hi:[1,0]
	v_pk_mul_f32 v[4:5], v[68:69], v[32:33] op_sel_hi:[1,0]
	v_pk_mul_f32 v[2:3], v[2:3], v[220:221]
	v_pk_mul_f32 v[4:5], v[4:5], v[222:223]
	v_cvt_pk_bf16_f32 v2, v2, v3
	v_cvt_pk_bf16_f32 v3, v4, v5
	global_store_dwordx2 v[30:31], v[2:3], off offset:224
	v_pk_mul_f32 v[6:7], v[66:67], v[32:33] op_sel_hi:[1,0]
	v_pk_mul_f32 v[8:9], v[16:17], v[32:33] op_sel_hi:[1,0]
	v_pk_mul_f32 v[2:3], v[6:7], v[224:225]
	v_pk_mul_f32 v[4:5], v[8:9], v[226:227]
	v_cvt_pk_bf16_f32 v2, v2, v3
	v_cvt_pk_bf16_f32 v3, v4, v5
	global_store_dwordx2 v[30:31], v[2:3], off offset:240
	s_branch .LBB0_451
